# stack + FFN-up epilogue: dead zero-inits in front of row-rotate DPP moves removed; attention prologue second-tile loads issued with the first
# speedup vs baseline: 1.0109x; 1.0073x over previous
; __device__ __forceinline__ int v_st(int k, int c) { const int kk = (k & ~0xC) | ((k & 4) << 1) | ((k & 8) >> 1); return ((kk >> 3) * 4 + (c >> 5)) * 512 + ((kk & 7) * 32 + (c & 31)) * 2; }
; __device__ __forceinline__ int v_rd_base(int lane) { return ((lane & 3) << 3) | (((lane >> 2) & 3) << 6) | (((lane >> 4) & 1) << 5) | (((lane >> 5) & 1) << 8); }
; #define SLOADA(k0) do { vsA0 = *(const bf16x8*)(&Vh[(size_t)((k0) + sr) * LDP + sc]); vsA1 = *(const bf16x8*)(&Vh[(size_t)((k0) + 32 + sr) * LDP + sc]); \
;     ksA0 = *(const bf16x8*)(&Kh[(size_t)((k0) + sr) * LDP + sc]); ksA1 = *(const bf16x8*)(&Kh[(size_t)((k0) + 32 + sr) * LDP + sc]); } while (0)
; #define SLOADB(k0) do { vsB0 = *(const bf16x8*)(&Vh[(size_t)((k0) + sr) * LDP + sc]); vsB1 = *(const bf16x8*)(&Vh[(size_t)((k0) + 32 + sr) * LDP + sc]); \
;     ksB0 = *(const bf16x8*)(&Kh[(size_t)((k0) + sr) * LDP + sc]); ksB1 = *(const bf16x8*)(&Kh[(size_t)((k0) + 32 + sr) * LDP + sc]); } while (0)
; #define SWRITEA(b) do { *(bf16x8*)(V_lds + (b) * SHM_V + vst0) = vsA0; *(bf16x8*)(V_lds + (b) * SHM_V + vst1) = vsA1; const int kc = sc * 2; \
;     *(bf16x8*)(K_lds + (b) * SHM_K + KSWZ(sr, kc)) = ksA0; *(bf16x8*)(K_lds + (b) * SHM_K + KSWZ(32 + sr, kc)) = ksA1; } while (0)
; __device__ __forceinline__ void attn_unit(const bf16* __restrict__ P, bf16* __restrict__ MIXIN, const float* __restrict__ gn, int seq0, int h, int q0, int nt, float kmax0, float kmax1, float slope, float lam, char* lds) {
;     ...
;   const int sr = tid >> 4, sc = (tid & 15) * 8, vst0 = v_st(sr, sc), vst1 = v_st(32 + sr, sc);
;   const int vb0 = (int)(uintptr_t)V_lds + v_rd_base(lane);
;   const float nsl2 = -slope * 1.4426950408889634f;
;   const float dqb = (float)(qpos - 4 * hi);
;   const int cbase = mp * 64;
;   const int jlo_ = q0 >> 6, jhi_ = (q0 + 127) >> 6;
;   bf16x8 vsA0, vsA1, ksA0, ksA1, vsB0, vsB1, ksB0, ksB1;
;     ...
;   f32x16 pA0, pA1, pB0, pB1; bf16x8 pa0, pa1, pa2, pa3;
;   SLOADA(t0 * 64); asm volatile("s_waitcnt vmcnt(0)" ::: "memory"); SWRITEA(0); __syncthreads();
;   SLOADB((t0 + 1) * 64); if (t0 + 2 < t1) SLOADA((t0 + 2) * 64);
.LBB0_315:
	v_ashrrev_i32_e32 v2, 4, v229
	v_add_u32_e32 v3, 32, v2
	s_lshl_b32 s33, s6, 6
	v_lshlrev_b32_e32 v8, 3, v229
	v_add_u32_e32 v37, s33, v2
	v_add_u32_e32 v6, s33, v3
	v_and_b32_e32 v185, 0x78, v8
	v_mad_i64_i32 v[4:5], s[0:1], v37, s27, 0
	v_mad_i64_i32 v[6:7], s[0:1], v6, s27, 0
	v_or_b32_e32 v4, v4, v185
	v_or_b32_e32 v6, v6, v185
	v_lshl_add_u64 v[4:5], v[4:5], 1, s[24:25]
	v_lshl_add_u64 v[6:7], v[6:7], 1, s[24:25]
	s_barrier
	global_load_dwordx4 v[144:147], v[4:5], off offset:2048
	global_load_dwordx4 v[152:155], v[6:7], off offset:2048
	global_load_dwordx4 v[148:151], v[4:5], off offset:1024
	global_load_dwordx4 v[156:159], v[6:7], off offset:1024
	v_and_b32_e32 v5, 0xfffff0, v2
	v_lshlrev_b32_e32 v6, 1, v2
	v_lshrrev_b32_e32 v7, 1, v2
	v_and_b32_e32 v9, 3, v2
	v_and_or_b32 v5, v6, 8, v5
	v_and_or_b32 v6, v7, 4, v9
	v_and_b32_e32 v9, 0xfffff0, v3
	v_lshlrev_b32_e32 v11, 1, v3
	v_and_b32_e32 v4, 0x70, v229
	v_bfe_u32 v8, v8, 5, 2
	v_lshlrev_b32_e32 v10, 8, v2
	s_add_i32 s33, s33, 64
	v_lshlrev_b32_e32 v7, 1, v185
	v_lshlrev_b32_e32 v12, 8, v3
	v_lshrrev_b32_e32 v15, 1, v5
	v_and_or_b32 v9, v11, 8, v9
	v_add_u32_e32 v13, s33, v2
	v_bitop3_b32 v10, v7, v10, v4 bitop3:0xde
	v_bitop3_b32 v11, v7, v12, v4 bitop3:0xde
	v_or_b32_e32 v12, v15, v8
	v_lshrrev_b32_e32 v9, 1, v9
	v_add_u32_e32 v14, s33, v3
	v_lshlrev_b32_e32 v16, 6, v6
	v_and_b32_e32 v17, 48, v7
	v_mad_i64_i32 v[4:5], s[0:1], v13, s27, 0
	v_add_u32_e32 v237, 0, v10
	v_lshlrev_b32_e32 v10, 9, v12
	v_or_b32_e32 v8, v9, v8
	v_mad_i64_i32 v[6:7], s[0:1], v14, s27, 0
	v_or_b32_e32 v4, v4, v185
	v_or3_b32 v9, v10, v16, v17
	v_lshlrev_b32_e32 v8, 9, v8
	v_or_b32_e32 v6, v6, v185
	v_lshl_add_u64 v[4:5], v[4:5], 1, s[24:25]
	v_or3_b32 v8, v8, v16, v17
	v_add_u32_e32 v239, 0, v9
	v_add_u32_e32 v238, 0, v11
	v_lshl_add_u64 v[6:7], v[6:7], 1, s[24:25]
	global_load_dwordx4 v[160:163], v[4:5], off offset:2048
	global_load_dwordx4 v[164:167], v[4:5], off offset:1024
	global_load_dwordx4 v[168:171], v[6:7], off offset:2048
	global_load_dwordx4 v[172:175], v[6:7], off offset:1024
	s_waitcnt vmcnt(4)
	v_add_u32_e32 v240, 0, v8
	s_add_i32 s33, s6, 2
	s_cmp_lt_i32 s33, s3
	s_cselect_b64 s[0:1], -1, 0
	s_cmp_ge_i32 s33, s3
	s_waitcnt vmcnt(7)
	ds_write_b128 v239, v[144:147]
	s_waitcnt vmcnt(6)
	ds_write_b128 v240, v[152:155]
	s_waitcnt vmcnt(5)
	ds_write_b128 v237, v[148:151] offset:32768
	s_waitcnt vmcnt(4)
	ds_write_b128 v238, v[156:159] offset:32768
	s_waitcnt lgkmcnt(0)
	s_barrier
	s_cbranch_scc1 .LBB0_317
	s_lshl_b32 s76, s33, 6
	v_add_u32_e32 v2, s76, v2
	v_mad_i64_i32 v[4:5], s[72:73], v2, s27, 0
	v_add_u32_e32 v2, s76, v3
	v_or_b32_e32 v4, v4, v185
	v_mad_i64_i32 v[2:3], s[72:73], v2, s27, 0
	v_lshl_add_u64 v[4:5], v[4:5], 1, s[24:25]
	v_or_b32_e32 v2, v2, v185
	v_lshl_add_u64 v[2:3], v[2:3], 1, s[24:25]
	global_load_dwordx4 v[144:147], v[4:5], off offset:2048
	global_load_dwordx4 v[148:151], v[4:5], off offset:1024
	global_load_dwordx4 v[152:155], v[2:3], off offset:2048
	global_load_dwordx4 v[156:159], v[2:3], off offset:1024

; __device__ __forceinline__ unsigned cvt_pk_bf16(float lo, float hi) { unsigned r; asm volatile("v_cvt_pk_bf16_f32 %0, %1, %2" : "=v"(r) : "v"(lo), "v"(hi)); return r; }
; __device__ __forceinline__ float dpp_ror1(float v) { return __builtin_bit_cast(float, __builtin_amdgcn_update_dpp(0, __builtin_bit_cast(int, v), 0x121, 0xf, 0xf, false)); }
; __device__ __forceinline__ float dpp_ror15(float v) { return __builtin_bit_cast(float, __builtin_amdgcn_update_dpp(0, __builtin_bit_cast(int, v), 0x12F, 0xf, 0xf, false)); }
;     __device__ __forceinline__ void operator()(const f32x4 (&acc)[2][2][4][2], const Unit& u, int wr, int wc, int fr, int fq) const {
;     ...
;                 const float fzp = zp ? 0.f : 1.f, fzn = zn ? 0.f : 1.f;
; #pragma unroll
;                 for (int n = 0; n < 2; ++n) {
;                     const f32x4 g = acc[ai][0][m][n], up = acc[ai][1][m][n];
;                     f32x4 tp = g, tn = g;
;                     if (!fix) { const f32x4 gm = (m > 0) ? acc[ai][0][m - 1][n] : acc[ai ^ 1][0][3][n], gx = (m < 3) ? acc[ai][0][m + 1][n] : acc[ai ^ 1][0][0][n];
;                         tp = (fr == 15) ? gm : g; tn = (fr == 0) ? gx : g; }
;                     f32x4 gp, gn;
; #pragma unroll
;                     for (int j = 0; j < 4; ++j) { gp[j] = dpp_ror1(tp[j]); gn[j] = dpp_ror15(tn[j]); }
;                     const f32x4 cv = (w0[n] * fzp) * gp + (w1[n] * g + ((w2[n] * fzn) * gn + bb[n]));
;                     const f32x4 inner = cv * (cv * cv * 0.044715f + 1.0f) * (-2.0f * 0.7978845608028654f * 1.4426950408889634f);
;                     f32x4 sg;
; #pragma unroll
;                     for (int j = 0; j < 4; ++j) sg[j] = __builtin_amdgcn_rcpf(1.0f + __builtin_amdgcn_exp2f(inner[j]));
;                     res[n] = cv * sg * up;
;                 }
;                 if (valid) { u32x4 w; w.x = cvt_pk_bf16(res[0][0], res[0][1]); w.y = cvt_pk_bf16(res[0][2], res[0][3]); w.z = cvt_pk_bf16(res[1][0], res[1][1]); w.w = cvt_pk_bf16(res[1][2], res[1][3]);
;                     __builtin_nontemporal_store(w, (u32x4*)(ACT + (size_t)grow * 4096 + ch0)); }
.LBB0_631:
	s_and_b64 s[16:17], s[0:1], s[18:19]
	s_and_b64 s[18:19], s[4:5], s[18:19]
	v_cndmask_b32_e64 v188, v36, v140, s[18:19]
	v_cndmask_b32_e64 v184, v36, v12, s[16:17]
	v_cndmask_b32_e64 v185, v39, v143, s[18:19]
	v_cndmask_b32_e64 v186, v38, v142, s[18:19]
	v_cndmask_b32_e64 v187, v37, v141, s[18:19]
	v_mov_b32_dpp v196, v188 row_ror:15 row_mask:0xf bank_mask:0xf
	v_cndmask_b32_e64 v189, v28, v136, s[18:19]
	v_cndmask_b32_e64 v179, v39, v15, s[16:17]
	v_cndmask_b32_e64 v181, v38, v14, s[16:17]
	v_cndmask_b32_e64 v183, v37, v13, s[16:17]
	v_mov_b32_dpp v192, v184 row_ror:1 row_mask:0xf bank_mask:0xf
	v_mov_b32_dpp v197, v187 row_ror:15 row_mask:0xf bank_mask:0xf
	v_mov_b32_dpp v198, v186 row_ror:15 row_mask:0xf bank_mask:0xf
	v_mov_b32_dpp v199, v185 row_ror:15 row_mask:0xf bank_mask:0xf
	v_cndmask_b32_e64 v185, v28, v8, s[16:17]
	v_cndmask_b32_e64 v187, v30, v138, s[18:19]
	v_cndmask_b32_e64 v186, v29, v137, s[18:19]
	v_mov_b32_dpp v188, v189 row_ror:15 row_mask:0xf bank_mask:0xf
	v_mov_b32_dpp v193, v183 row_ror:1 row_mask:0xf bank_mask:0xf
	v_mov_b32_dpp v194, v181 row_ror:1 row_mask:0xf bank_mask:0xf
	v_mov_b32_dpp v195, v179 row_ror:1 row_mask:0xf bank_mask:0xf
	v_cndmask_b32_e64 v179, v31, v11, s[16:17]
	v_cndmask_b32_e64 v181, v30, v10, s[16:17]
	v_cndmask_b32_e64 v183, v29, v9, s[16:17]
	v_cndmask_b32_e64 v212, v31, v139, s[18:19]
	v_mov_b32_dpp v184, v185 row_ror:1 row_mask:0xf bank_mask:0xf
	v_mov_b32_dpp v189, v186 row_ror:15 row_mask:0xf bank_mask:0xf
	v_mov_b32_dpp v190, v187 row_ror:15 row_mask:0xf bank_mask:0xf
	v_mov_b32_dpp v185, v183 row_ror:1 row_mask:0xf bank_mask:0xf
	v_mov_b32_dpp v186, v181 row_ror:1 row_mask:0xf bank_mask:0xf
	v_mov_b32_dpp v187, v179 row_ror:1 row_mask:0xf bank_mask:0xf
	v_mov_b32_dpp v191, v212 row_ror:15 row_mask:0xf bank_mask:0xf
	s_and_saveexec_b64 s[20:21], s[82:83]
	s_cbranch_execz .LBB0_633
	s_waitcnt vmcnt(0)
	v_pk_mul_f32 v[218:219], v[96:97], v[180:181] op_sel_hi:[1,0]
	v_pk_mul_f32 v[214:215], v[88:89], v[182:183] op_sel_hi:[1,0]
	v_pk_fma_f32 v[196:197], v[218:219], v[196:197], v[100:101]
	v_pk_mul_f32 v[216:217], v[98:99], v[180:181] op_sel_hi:[1,0]
	v_pk_fma_f32 v[196:197], v[36:37], v[92:93], v[196:197]
	v_pk_fma_f32 v[198:199], v[216:217], v[198:199], v[102:103]
	v_pk_fma_f32 v[192:193], v[214:215], v[192:193], v[196:197]
	v_pk_mul_f32 v[212:213], v[90:91], v[182:183] op_sel_hi:[1,0]
	v_pk_mul_f32 v[196:197], v[192:193], v[192:193]
	v_pk_fma_f32 v[198:199], v[38:39], v[94:95], v[198:199]
	v_fma_f32 v179, v196, s97, 1.0
	v_mul_f32_e32 v179, v192, v179
	v_mul_f32_e32 v179, 0xc0135761, v179
	v_exp_f32_e32 v179, v179
	v_pk_fma_f32 v[194:195], v[212:213], v[194:195], v[198:199]
	v_add_f32_e32 v179, 1.0, v179
	v_pk_mul_f32 v[198:199], v[194:195], v[194:195]
	v_rcp_f32_e32 v196, v179
	v_fma_f32 v181, v198, s97, 1.0
	v_mul_f32_e32 v181, v194, v181
	v_fma_f32 v183, v199, s97, 1.0
	v_mul_f32_e32 v181, 0xc0135761, v181
	v_mul_f32_e32 v183, v195, v183
	v_fma_f32 v179, v197, s97, 1.0
	v_exp_f32_e32 v181, v181
	v_mul_f32_e32 v183, 0xc0135761, v183
	v_mul_f32_e32 v179, v193, v179
	v_exp_f32_e32 v183, v183
	v_mul_f32_e32 v179, 0xc0135761, v179
	v_exp_f32_e32 v179, v179
	v_add_f32_e32 v181, 1.0, v181
	v_rcp_f32_e32 v198, v181
	v_add_f32_e32 v181, 1.0, v183
	v_rcp_f32_e32 v199, v181
	v_add_f32_e32 v179, 1.0, v179
	v_rcp_f32_e32 v197, v179
	v_pk_mul_f32 v[194:195], v[194:195], v[198:199]
	v_pk_mul_f32 v[198:199], v[82:83], v[180:181] op_sel_hi:[1,0]
	v_pk_mul_f32 v[180:181], v[80:81], v[180:181] op_sel_hi:[1,0]
	v_pk_mul_f32 v[192:193], v[192:193], v[196:197]
	v_pk_fma_f32 v[180:181], v[180:181], v[188:189], v[84:85]
	v_pk_mul_f32 v[196:197], v[74:75], v[182:183] op_sel_hi:[1,0]
	v_pk_mul_f32 v[182:183], v[72:73], v[182:183] op_sel_hi:[1,0]
	v_pk_fma_f32 v[180:181], v[28:29], v[76:77], v[180:181]
	v_pk_fma_f32 v[190:191], v[198:199], v[190:191], v[86:87]
	v_pk_fma_f32 v[180:181], v[182:183], v[184:185], v[180:181]
	v_pk_fma_f32 v[184:185], v[30:31], v[78:79], v[190:191]
	v_pk_mul_f32 v[182:183], v[180:181], v[180:181]
	v_pk_fma_f32 v[184:185], v[196:197], v[186:187], v[184:185]
	v_fma_f32 v179, v182, s97, 1.0
	v_mul_f32_e32 v179, v180, v179
	v_mul_f32_e32 v179, 0xc0135761, v179
	v_exp_f32_e32 v179, v179
	v_pk_mul_f32 v[186:187], v[184:185], v[184:185]
	v_pk_mul_f32 v[156:157], v[156:157], v[192:193]
	v_pk_mul_f32 v[158:159], v[158:159], v[194:195]
	v_add_f32_e32 v179, 1.0, v179
	v_rcp_f32_e32 v182, v179
	v_fma_f32 v179, v183, s97, 1.0
	v_fma_f32 v183, v186, s97, 1.0
	v_mul_f32_e32 v183, v184, v183
	v_fma_f32 v186, v187, s97, 1.0
	v_mul_f32_e32 v179, v181, v179
	v_mul_f32_e32 v183, 0xc0135761, v183
	v_mul_f32_e32 v186, v185, v186
	v_mul_f32_e32 v179, 0xc0135761, v179
	v_exp_f32_e32 v183, v183
	v_mul_f32_e32 v186, 0xc0135761, v186
	v_exp_f32_e32 v179, v179
	v_exp_f32_e32 v187, v186
	v_add_f32_e32 v183, 1.0, v183
	v_rcp_f32_e32 v186, v183
	v_add_f32_e32 v179, 1.0, v179
	v_add_f32_e32 v183, 1.0, v187
	v_rcp_f32_e32 v187, v183
	v_rcp_f32_e32 v183, v179
	v_ashrrev_i32_e32 v179, 31, v178
	v_pk_mul_f32 v[184:185], v[184:185], v[186:187]
	v_pk_mul_f32 v[180:181], v[180:181], v[182:183]
	v_pk_mul_f32 v[182:183], v[154:155], v[184:185]
	v_pk_mul_f32 v[154:155], v[152:153], v[180:181]
	v_cvt_pk_bf16_f32 v152, v156, v157
	v_lshlrev_b64 v[156:157], 13, v[178:179]
	v_lshl_add_u64 v[156:157], s[44:45], 0, v[156:157]
	v_lshl_add_u64 v[156:157], v[176:177], 1, v[156:157]
	v_cvt_pk_bf16_f32 v153, v158, v159
	v_cvt_pk_bf16_f32 v154, v154, v155
	v_cvt_pk_bf16_f32 v155, v182, v183
	global_store_dwordx4 v[156:157], v[152:155], off nt

; __device__ __forceinline__ unsigned cvt_pk_bf16(float lo, float hi) { unsigned r; asm volatile("v_cvt_pk_bf16_f32 %0, %1, %2" : "=v"(r) : "v"(lo), "v"(hi)); return r; }
; __device__ __forceinline__ float dpp_ror1(float v) { return __builtin_bit_cast(float, __builtin_amdgcn_update_dpp(0, __builtin_bit_cast(int, v), 0x121, 0xf, 0xf, false)); }
; __device__ __forceinline__ float dpp_ror15(float v) { return __builtin_bit_cast(float, __builtin_amdgcn_update_dpp(0, __builtin_bit_cast(int, v), 0x12F, 0xf, 0xf, false)); }
;     __device__ __forceinline__ void operator()(const f32x4 (&acc)[2][2][4][2], const Unit& u, int wr, int wc, int fr, int fq) const {
;     ...
;                 const float fzp = zp ? 0.f : 1.f, fzn = zn ? 0.f : 1.f;
; #pragma unroll
;                 for (int n = 0; n < 2; ++n) {
;                     const f32x4 g = acc[ai][0][m][n], up = acc[ai][1][m][n];
;                     f32x4 tp = g, tn = g;
;                     if (!fix) { const f32x4 gm = (m > 0) ? acc[ai][0][m - 1][n] : acc[ai ^ 1][0][3][n], gx = (m < 3) ? acc[ai][0][m + 1][n] : acc[ai ^ 1][0][0][n];
;                         tp = (fr == 15) ? gm : g; tn = (fr == 0) ? gx : g; }
;                     f32x4 gp, gn;
; #pragma unroll
;                     for (int j = 0; j < 4; ++j) { gp[j] = dpp_ror1(tp[j]); gn[j] = dpp_ror15(tn[j]); }
;                     const f32x4 cv = (w0[n] * fzp) * gp + (w1[n] * g + ((w2[n] * fzn) * gn + bb[n]));
;                     const f32x4 inner = cv * (cv * cv * 0.044715f + 1.0f) * (-2.0f * 0.7978845608028654f * 1.4426950408889634f);
;                     f32x4 sg;
; #pragma unroll
;                     for (int j = 0; j < 4; ++j) sg[j] = __builtin_amdgcn_rcpf(1.0f + __builtin_amdgcn_exp2f(inner[j]));
;                     res[n] = cv * sg * up;
;                 }
;                 if (valid) { u32x4 w; w.x = cvt_pk_bf16(res[0][0], res[0][1]); w.y = cvt_pk_bf16(res[0][2], res[0][3]); w.z = cvt_pk_bf16(res[1][0], res[1][1]); w.w = cvt_pk_bf16(res[1][2], res[1][3]);
;                     __builtin_nontemporal_store(w, (u32x4*)(ACT + (size_t)grow * 4096 + ch0)); }
.LBB0_639:
	v_cndmask_b32_e64 v154, v142, v38, s[16:17]
	v_cndmask_b32_e64 v155, v141, v37, s[16:17]
	v_cndmask_b32_e64 v158, v142, v126, s[18:19]
	v_cndmask_b32_e64 v159, v141, v125, s[18:19]
	v_cndmask_b32_e64 v156, v140, v36, s[16:17]
	v_cndmask_b32_e64 v178, v140, v124, s[18:19]
	v_mov_b32_dpp v181, v155 row_ror:1 row_mask:0xf bank_mask:0xf
	v_mov_b32_dpp v185, v159 row_ror:15 row_mask:0xf bank_mask:0xf
	v_mov_b32_dpp v182, v154 row_ror:1 row_mask:0xf bank_mask:0xf
	v_mov_b32_dpp v186, v158 row_ror:15 row_mask:0xf bank_mask:0xf
	v_cndmask_b32_e64 v155, v136, v28, s[16:17]
	v_cndmask_b32_e64 v159, v136, v120, s[18:19]
	v_cndmask_b32_e64 v157, v143, v127, s[18:19]
	v_mov_b32_dpp v180, v156 row_ror:1 row_mask:0xf bank_mask:0xf
	v_mov_b32_dpp v184, v178 row_ror:15 row_mask:0xf bank_mask:0xf
	v_cndmask_b32_e64 v156, v137, v29, s[16:17]
	v_cndmask_b32_e64 v178, v137, v121, s[18:19]
	v_mov_b32_dpp v154, v155 row_ror:1 row_mask:0xf bank_mask:0xf
	v_mov_b32_dpp v158, v159 row_ror:15 row_mask:0xf bank_mask:0xf
	v_cndmask_b32_e64 v153, v143, v39, s[16:17]
	v_mov_b32_dpp v187, v157 row_ror:15 row_mask:0xf bank_mask:0xf
	v_cndmask_b32_e64 v157, v138, v30, s[16:17]
	v_cndmask_b32_e64 v179, v138, v122, s[18:19]
	v_mov_b32_dpp v155, v156 row_ror:1 row_mask:0xf bank_mask:0xf
	v_mov_b32_dpp v159, v178 row_ror:15 row_mask:0xf bank_mask:0xf
	v_mov_b32_dpp v183, v153 row_ror:1 row_mask:0xf bank_mask:0xf
	v_cndmask_b32_e64 v153, v139, v31, s[16:17]
	v_cndmask_b32_e64 v189, v139, v123, s[18:19]
	v_mov_b32_dpp v156, v157 row_ror:1 row_mask:0xf bank_mask:0xf
	v_mov_b32_dpp v178, v179 row_ror:15 row_mask:0xf bank_mask:0xf
	s_nop 0
	v_mov_b32_dpp v157, v153 row_ror:1 row_mask:0xf bank_mask:0xf
	v_mov_b32_dpp v179, v189 row_ror:15 row_mask:0xf bank_mask:0xf
	s_and_saveexec_b64 s[80:81], s[82:83]
	s_cbranch_execz .LBB0_641
	s_waitcnt vmcnt(0)
	v_pk_fma_f32 v[184:185], v[96:97], v[184:185], v[100:101]
	v_pk_fma_f32 v[186:187], v[98:99], v[186:187], v[102:103]
	v_pk_fma_f32 v[184:185], v[140:141], v[92:93], v[184:185]
	v_pk_fma_f32 v[186:187], v[142:143], v[94:95], v[186:187]
	v_pk_fma_f32 v[180:181], v[88:89], v[180:181], v[184:185]
	v_pk_fma_f32 v[182:183], v[90:91], v[182:183], v[186:187]
	v_pk_mul_f32 v[184:185], v[180:181], v[180:181]
	v_pk_mul_f32 v[186:187], v[182:183], v[182:183]
	v_fma_f32 v153, v184, s97, 1.0
	v_mul_f32_e32 v153, v180, v153
	v_mul_f32_e32 v153, 0xc0135761, v153
	v_exp_f32_e32 v153, v153
	v_pk_fma_f32 v[158:159], v[80:81], v[158:159], v[84:85]
	v_pk_fma_f32 v[178:179], v[82:83], v[178:179], v[86:87]
	v_pk_fma_f32 v[158:159], v[136:137], v[76:77], v[158:159]
	v_add_f32_e32 v153, 1.0, v153
	v_rcp_f32_e32 v184, v153
	v_fma_f32 v153, v185, s97, 1.0
	v_fma_f32 v185, v186, s97, 1.0
	v_mul_f32_e32 v185, v182, v185
	v_fma_f32 v186, v187, s97, 1.0
	v_mul_f32_e32 v153, v181, v153
	v_mul_f32_e32 v185, 0xc0135761, v185
	v_mul_f32_e32 v186, v183, v186
	v_mul_f32_e32 v153, 0xc0135761, v153
	v_exp_f32_e32 v185, v185
	v_mul_f32_e32 v186, 0xc0135761, v186
	v_exp_f32_e32 v153, v153
	v_exp_f32_e32 v187, v186
	v_add_f32_e32 v185, 1.0, v185
	v_pk_fma_f32 v[154:155], v[72:73], v[154:155], v[158:159]
	v_add_f32_e32 v153, 1.0, v153
	v_rcp_f32_e32 v186, v185
	v_add_f32_e32 v185, 1.0, v187
	v_pk_mul_f32 v[158:159], v[154:155], v[154:155]
	v_rcp_f32_e32 v187, v185
	v_rcp_f32_e32 v185, v153
	v_fma_f32 v153, v158, s97, 1.0
	v_mul_f32_e32 v153, v154, v153
	v_mul_f32_e32 v153, 0xc0135761, v153
	v_exp_f32_e32 v153, v153
	v_pk_fma_f32 v[178:179], v[138:139], v[78:79], v[178:179]
	v_pk_mul_f32 v[180:181], v[180:181], v[184:185]
	v_pk_fma_f32 v[156:157], v[74:75], v[156:157], v[178:179]
	v_add_f32_e32 v153, 1.0, v153
	v_pk_mul_f32 v[178:179], v[156:157], v[156:157]
	v_rcp_f32_e32 v158, v153
	v_fma_f32 v153, v159, s97, 1.0
	v_fma_f32 v159, v178, s97, 1.0
	v_mul_f32_e32 v159, v156, v159
	v_fma_f32 v178, v179, s97, 1.0
	v_mul_f32_e32 v153, v155, v153
	v_mul_f32_e32 v159, 0xc0135761, v159
	v_mul_f32_e32 v178, v157, v178
	v_mul_f32_e32 v153, 0xc0135761, v153
	v_exp_f32_e32 v159, v159
	v_mul_f32_e32 v178, 0xc0135761, v178
	v_exp_f32_e32 v153, v153
	v_exp_f32_e32 v179, v178
	v_add_f32_e32 v159, 1.0, v159
	v_rcp_f32_e32 v178, v159
	v_add_f32_e32 v153, 1.0, v153
	v_add_f32_e32 v159, 1.0, v179
	v_rcp_f32_e32 v179, v159
	v_rcp_f32_e32 v159, v153
	v_pk_mul_f32 v[148:149], v[148:149], v[180:181]
	v_ashrrev_i32_e32 v153, 31, v152
	v_pk_mul_f32 v[156:157], v[156:157], v[178:179]
	v_pk_mul_f32 v[154:155], v[154:155], v[158:159]
	v_pk_mul_f32 v[156:157], v[146:147], v[156:157]
	v_pk_mul_f32 v[146:147], v[144:145], v[154:155]
	v_cvt_pk_bf16_f32 v144, v148, v149
	v_lshlrev_b64 v[148:149], 13, v[152:153]
	v_lshl_add_u64 v[148:149], s[44:45], 0, v[148:149]
	v_pk_mul_f32 v[182:183], v[182:183], v[186:187]
	v_lshl_add_u64 v[148:149], v[176:177], 1, v[148:149]
	v_pk_mul_f32 v[150:151], v[150:151], v[182:183]
	s_nop 0
	v_cvt_pk_bf16_f32 v145, v150, v151
	v_cvt_pk_bf16_f32 v146, v146, v147
	v_cvt_pk_bf16_f32 v147, v156, v157
	global_store_dwordx4 v[148:149], v[144:147], off nt

; __device__ __forceinline__ unsigned cvt_pk_bf16(float lo, float hi) { unsigned r; asm volatile("v_cvt_pk_bf16_f32 %0, %1, %2" : "=v"(r) : "v"(lo), "v"(hi)); return r; }
; __device__ __forceinline__ float dpp_ror1(float v) { return __builtin_bit_cast(float, __builtin_amdgcn_update_dpp(0, __builtin_bit_cast(int, v), 0x121, 0xf, 0xf, false)); }
; __device__ __forceinline__ float dpp_ror15(float v) { return __builtin_bit_cast(float, __builtin_amdgcn_update_dpp(0, __builtin_bit_cast(int, v), 0x12F, 0xf, 0xf, false)); }
;     __device__ __forceinline__ void operator()(const f32x4 (&acc)[2][2][4][2], const Unit& u, int wr, int wc, int fr, int fq) const {
;     ...
;                 const float fzp = zp ? 0.f : 1.f, fzn = zn ? 0.f : 1.f;
; #pragma unroll
;                 for (int n = 0; n < 2; ++n) {
;                     const f32x4 g = acc[ai][0][m][n], up = acc[ai][1][m][n];
;                     f32x4 tp = g, tn = g;
;                     if (!fix) { const f32x4 gm = (m > 0) ? acc[ai][0][m - 1][n] : acc[ai ^ 1][0][3][n], gx = (m < 3) ? acc[ai][0][m + 1][n] : acc[ai ^ 1][0][0][n];
;                         tp = (fr == 15) ? gm : g; tn = (fr == 0) ? gx : g; }
;                     f32x4 gp, gn;
; #pragma unroll
;                     for (int j = 0; j < 4; ++j) { gp[j] = dpp_ror1(tp[j]); gn[j] = dpp_ror15(tn[j]); }
;                     const f32x4 cv = (w0[n] * fzp) * gp + (w1[n] * g + ((w2[n] * fzn) * gn + bb[n]));
;                     const f32x4 inner = cv * (cv * cv * 0.044715f + 1.0f) * (-2.0f * 0.7978845608028654f * 1.4426950408889634f);
;                     f32x4 sg;
; #pragma unroll
;                     for (int j = 0; j < 4; ++j) sg[j] = __builtin_amdgcn_rcpf(1.0f + __builtin_amdgcn_exp2f(inner[j]));
;                     res[n] = cv * sg * up;
;                 }
;                 if (valid) { u32x4 w; w.x = cvt_pk_bf16(res[0][0], res[0][1]); w.y = cvt_pk_bf16(res[0][2], res[0][3]); w.z = cvt_pk_bf16(res[1][0], res[1][1]); w.w = cvt_pk_bf16(res[1][2], res[1][3]);
;                     __builtin_nontemporal_store(w, (u32x4*)(ACT + (size_t)grow * 4096 + ch0)); }
.LBB0_647:
	v_cndmask_b32_e64 v149, v126, v110, s[18:19]
	v_cndmask_b32_e64 v143, v127, v143, s[16:17]
	v_cndmask_b32_e64 v147, v124, v108, s[18:19]
	v_mov_b32_dpp v152, v149 row_ror:15 row_mask:0xf bank_mask:0xf
	v_cndmask_b32_e64 v141, v125, v141, s[16:17]
	v_mov_b32_dpp v149, v143 row_ror:1 row_mask:0xf bank_mask:0xf
	v_cndmask_b32_e64 v143, v123, v139, s[16:17]
	v_cndmask_b32_e64 v139, v122, v138, s[16:17]
	v_cndmask_b32_e64 v138, v121, v137, s[16:17]
	v_cndmask_b32_e64 v137, v120, v136, s[16:17]
	v_cndmask_b32_e64 v140, v124, v140, s[16:17]
	v_cndmask_b32_e64 v148, v125, v109, s[18:19]
	v_mov_b32_dpp v150, v147 row_ror:15 row_mask:0xf bank_mask:0xf
	v_mov_b32_dpp v136, v137 row_ror:1 row_mask:0xf bank_mask:0xf
	v_cndmask_b32_e64 v142, v126, v142, s[16:17]
	v_mov_b32_dpp v146, v140 row_ror:1 row_mask:0xf bank_mask:0xf
	v_mov_b32_dpp v147, v141 row_ror:1 row_mask:0xf bank_mask:0xf
	v_mov_b32_dpp v151, v148 row_ror:15 row_mask:0xf bank_mask:0xf
	v_cndmask_b32_e64 v141, v120, v104, s[18:19]
	v_mov_b32_dpp v137, v138 row_ror:1 row_mask:0xf bank_mask:0xf
	v_cndmask_b32_e64 v145, v127, v111, s[18:19]
	v_mov_b32_dpp v148, v142 row_ror:1 row_mask:0xf bank_mask:0xf
	v_cndmask_b32_e64 v142, v121, v105, s[18:19]
	v_mov_b32_dpp v140, v141 row_ror:15 row_mask:0xf bank_mask:0xf
	v_mov_b32_dpp v138, v139 row_ror:1 row_mask:0xf bank_mask:0xf
	v_mov_b32_dpp v153, v145 row_ror:15 row_mask:0xf bank_mask:0xf
	v_cndmask_b32_e64 v145, v123, v107, s[18:19]
	v_cndmask_b32_e64 v154, v122, v106, s[18:19]
	v_mov_b32_dpp v141, v142 row_ror:15 row_mask:0xf bank_mask:0xf
	v_mov_b32_dpp v139, v143 row_ror:1 row_mask:0xf bank_mask:0xf
	v_mov_b32_dpp v142, v154 row_ror:15 row_mask:0xf bank_mask:0xf
	s_nop 0
	v_mov_b32_dpp v143, v145 row_ror:15 row_mask:0xf bank_mask:0xf
	s_and_saveexec_b64 s[80:81], s[82:83]
	s_cbranch_execz .LBB0_649
	s_waitcnt vmcnt(0)
	v_pk_fma_f32 v[150:151], v[96:97], v[150:151], v[100:101]
	v_pk_fma_f32 v[152:153], v[98:99], v[152:153], v[102:103]
	v_pk_fma_f32 v[150:151], v[124:125], v[92:93], v[150:151]
	v_pk_fma_f32 v[152:153], v[126:127], v[94:95], v[152:153]
	v_pk_fma_f32 v[146:147], v[88:89], v[146:147], v[150:151]
	v_pk_fma_f32 v[148:149], v[90:91], v[148:149], v[152:153]
	v_pk_mul_f32 v[150:151], v[146:147], v[146:147]
	v_pk_fma_f32 v[142:143], v[82:83], v[142:143], v[86:87]
	v_fma_f32 v145, v150, s97, 1.0
	v_mul_f32_e32 v145, v146, v145
	v_mul_f32_e32 v145, 0xc0135761, v145
	v_exp_f32_e32 v145, v145
	v_pk_fma_f32 v[140:141], v[80:81], v[140:141], v[84:85]
	v_pk_mul_f32 v[152:153], v[148:149], v[148:149]
	v_pk_fma_f32 v[140:141], v[120:121], v[76:77], v[140:141]
	v_add_f32_e32 v145, 1.0, v145
	v_pk_fma_f32 v[142:143], v[122:123], v[78:79], v[142:143]
	v_rcp_f32_e32 v150, v145
	v_fma_f32 v145, v151, s97, 1.0
	v_fma_f32 v151, v152, s97, 1.0
	v_pk_fma_f32 v[136:137], v[72:73], v[136:137], v[140:141]
	v_pk_fma_f32 v[138:139], v[74:75], v[138:139], v[142:143]
	v_mul_f32_e32 v151, v148, v151
	v_fma_f32 v152, v153, s97, 1.0
	v_pk_mul_f32 v[140:141], v[136:137], v[136:137]
	v_pk_mul_f32 v[142:143], v[138:139], v[138:139]
	v_mul_f32_e32 v145, v147, v145
	v_mul_f32_e32 v151, 0xc0135761, v151
	v_mul_f32_e32 v152, v149, v152
	v_fma_f32 v140, v140, s97, 1.0
	v_fma_f32 v141, v141, s97, 1.0
	v_fma_f32 v142, v142, s97, 1.0
	v_fma_f32 v143, v143, s97, 1.0
	v_mul_f32_e32 v145, 0xc0135761, v145
	v_exp_f32_e32 v151, v151
	v_mul_f32_e32 v152, 0xc0135761, v152
	v_mul_f32_e32 v140, v136, v140
	v_mul_f32_e32 v141, v137, v141
	v_mul_f32_e32 v142, v138, v142
	v_mul_f32_e32 v143, v139, v143
	v_exp_f32_e32 v145, v145
	v_exp_f32_e32 v153, v152
	v_mul_f32_e32 v140, 0xc0135761, v140
	v_mul_f32_e32 v141, 0xc0135761, v141
	v_mul_f32_e32 v142, 0xc0135761, v142
	v_mul_f32_e32 v143, 0xc0135761, v143
	v_exp_f32_e32 v140, v140
	v_exp_f32_e32 v141, v141
	v_exp_f32_e32 v142, v142
	v_exp_f32_e32 v143, v143
	v_add_f32_e32 v151, 1.0, v151
	v_add_f32_e32 v145, 1.0, v145
	v_rcp_f32_e32 v152, v151
	v_add_f32_e32 v151, 1.0, v153
	v_rcp_f32_e32 v153, v151
	v_rcp_f32_e32 v151, v145
	v_add_f32_e32 v140, 1.0, v140
	v_add_f32_e32 v141, 1.0, v141
	v_add_f32_e32 v142, 1.0, v142
	v_add_f32_e32 v143, 1.0, v143
	v_rcp_f32_e32 v140, v140
	v_rcp_f32_e32 v142, v142
	v_rcp_f32_e32 v143, v143
	v_rcp_f32_e32 v141, v141
	v_pk_mul_f32 v[146:147], v[146:147], v[150:151]
	v_ashrrev_i32_e32 v145, 31, v144
	v_pk_mul_f32 v[132:133], v[132:133], v[146:147]
	v_pk_mul_f32 v[138:139], v[138:139], v[142:143]
	v_pk_mul_f32 v[136:137], v[136:137], v[140:141]
	v_pk_mul_f32 v[138:139], v[130:131], v[138:139]
	v_pk_mul_f32 v[130:131], v[128:129], v[136:137]
	v_cvt_pk_bf16_f32 v128, v132, v133
	v_lshlrev_b64 v[132:133], 13, v[144:145]
	v_lshl_add_u64 v[132:133], s[44:45], 0, v[132:133]
	v_pk_mul_f32 v[148:149], v[148:149], v[152:153]
	v_lshl_add_u64 v[132:133], v[176:177], 1, v[132:133]
	v_pk_mul_f32 v[134:135], v[134:135], v[148:149]
	s_nop 0
	v_cvt_pk_bf16_f32 v129, v134, v135
	v_cvt_pk_bf16_f32 v130, v130, v131
	v_cvt_pk_bf16_f32 v131, v138, v139
	global_store_dwordx4 v[132:133], v[128:131], off nt

; __device__ __forceinline__ unsigned cvt_pk_bf16(float lo, float hi) { unsigned r; asm volatile("v_cvt_pk_bf16_f32 %0, %1, %2" : "=v"(r) : "v"(lo), "v"(hi)); return r; }
; __device__ __forceinline__ float dpp_ror1(float v) { return __builtin_bit_cast(float, __builtin_amdgcn_update_dpp(0, __builtin_bit_cast(int, v), 0x121, 0xf, 0xf, false)); }
; __device__ __forceinline__ float dpp_ror15(float v) { return __builtin_bit_cast(float, __builtin_amdgcn_update_dpp(0, __builtin_bit_cast(int, v), 0x12F, 0xf, 0xf, false)); }
;     __device__ __forceinline__ void operator()(const f32x4 (&acc)[2][2][4][2], const Unit& u, int wr, int wc, int fr, int fq) const {
;     ...
;                 const float fzp = zp ? 0.f : 1.f, fzn = zn ? 0.f : 1.f;
; #pragma unroll
;                 for (int n = 0; n < 2; ++n) {
;                     const f32x4 g = acc[ai][0][m][n], up = acc[ai][1][m][n];
;                     f32x4 tp = g, tn = g;
;                     if (!fix) { const f32x4 gm = (m > 0) ? acc[ai][0][m - 1][n] : acc[ai ^ 1][0][3][n], gx = (m < 3) ? acc[ai][0][m + 1][n] : acc[ai ^ 1][0][0][n];
;                         tp = (fr == 15) ? gm : g; tn = (fr == 0) ? gx : g; }
;                     f32x4 gp, gn;
; #pragma unroll
;                     for (int j = 0; j < 4; ++j) { gp[j] = dpp_ror1(tp[j]); gn[j] = dpp_ror15(tn[j]); }
;                     const f32x4 cv = (w0[n] * fzp) * gp + (w1[n] * g + ((w2[n] * fzn) * gn + bb[n]));
;                     const f32x4 inner = cv * (cv * cv * 0.044715f + 1.0f) * (-2.0f * 0.7978845608028654f * 1.4426950408889634f);
;                     f32x4 sg;
; #pragma unroll
;                     for (int j = 0; j < 4; ++j) sg[j] = __builtin_amdgcn_rcpf(1.0f + __builtin_amdgcn_exp2f(inner[j]));
;                     res[n] = cv * sg * up;
;                 }
;                 if (valid) { u32x4 w; w.x = cvt_pk_bf16(res[0][0], res[0][1]); w.y = cvt_pk_bf16(res[0][2], res[0][3]); w.z = cvt_pk_bf16(res[1][0], res[1][1]); w.w = cvt_pk_bf16(res[1][2], res[1][3]);
;                     __builtin_nontemporal_store(w, (u32x4*)(ACT + (size_t)grow * 4096 + ch0)); }
.LBB0_655:
	v_cndmask_b32_e64 v133, v110, v62, s[18:19]
	v_cndmask_b32_e64 v127, v111, v127, s[16:17]
	v_cndmask_b32_e64 v131, v108, v60, s[18:19]
	v_mov_b32_dpp v136, v133 row_ror:15 row_mask:0xf bank_mask:0xf
	v_cndmask_b32_e64 v125, v109, v125, s[16:17]
	v_mov_b32_dpp v133, v127 row_ror:1 row_mask:0xf bank_mask:0xf
	v_cndmask_b32_e64 v127, v107, v123, s[16:17]
	v_cndmask_b32_e64 v123, v106, v122, s[16:17]
	v_cndmask_b32_e64 v122, v105, v121, s[16:17]
	v_cndmask_b32_e64 v121, v104, v120, s[16:17]
	v_cndmask_b32_e64 v124, v108, v124, s[16:17]
	v_cndmask_b32_e64 v132, v109, v61, s[18:19]
	v_mov_b32_dpp v134, v131 row_ror:15 row_mask:0xf bank_mask:0xf
	v_mov_b32_dpp v120, v121 row_ror:1 row_mask:0xf bank_mask:0xf
	v_cndmask_b32_e64 v126, v110, v126, s[16:17]
	v_mov_b32_dpp v130, v124 row_ror:1 row_mask:0xf bank_mask:0xf
	v_mov_b32_dpp v131, v125 row_ror:1 row_mask:0xf bank_mask:0xf
	v_mov_b32_dpp v135, v132 row_ror:15 row_mask:0xf bank_mask:0xf
	v_cndmask_b32_e64 v125, v104, v56, s[18:19]
	v_mov_b32_dpp v121, v122 row_ror:1 row_mask:0xf bank_mask:0xf
	v_cndmask_b32_e64 v129, v111, v63, s[18:19]
	v_mov_b32_dpp v132, v126 row_ror:1 row_mask:0xf bank_mask:0xf
	v_cndmask_b32_e64 v126, v105, v57, s[18:19]
	v_mov_b32_dpp v124, v125 row_ror:15 row_mask:0xf bank_mask:0xf
	v_mov_b32_dpp v122, v123 row_ror:1 row_mask:0xf bank_mask:0xf
	v_mov_b32_dpp v137, v129 row_ror:15 row_mask:0xf bank_mask:0xf
	v_cndmask_b32_e64 v129, v107, v59, s[18:19]
	v_cndmask_b32_e64 v138, v106, v58, s[18:19]
	v_mov_b32_dpp v125, v126 row_ror:15 row_mask:0xf bank_mask:0xf
	v_mov_b32_dpp v123, v127 row_ror:1 row_mask:0xf bank_mask:0xf
	v_mov_b32_dpp v126, v138 row_ror:15 row_mask:0xf bank_mask:0xf
	s_nop 0
	v_mov_b32_dpp v127, v129 row_ror:15 row_mask:0xf bank_mask:0xf
	s_and_saveexec_b64 s[80:81], s[82:83]
	s_cbranch_execz .LBB0_657
	s_waitcnt vmcnt(0)
	v_pk_fma_f32 v[134:135], v[96:97], v[134:135], v[100:101]
	v_pk_fma_f32 v[136:137], v[98:99], v[136:137], v[102:103]
	v_pk_fma_f32 v[134:135], v[108:109], v[92:93], v[134:135]
	v_pk_fma_f32 v[136:137], v[110:111], v[94:95], v[136:137]
	v_pk_fma_f32 v[130:131], v[88:89], v[130:131], v[134:135]
	v_pk_fma_f32 v[132:133], v[90:91], v[132:133], v[136:137]
	v_pk_mul_f32 v[134:135], v[130:131], v[130:131]
	v_pk_fma_f32 v[126:127], v[82:83], v[126:127], v[86:87]
	v_fma_f32 v129, v134, s97, 1.0
	v_mul_f32_e32 v129, v130, v129
	v_mul_f32_e32 v129, 0xc0135761, v129
	v_exp_f32_e32 v129, v129
	v_pk_fma_f32 v[124:125], v[80:81], v[124:125], v[84:85]
	v_pk_mul_f32 v[136:137], v[132:133], v[132:133]
	v_pk_fma_f32 v[124:125], v[104:105], v[76:77], v[124:125]
	v_add_f32_e32 v129, 1.0, v129
	v_pk_fma_f32 v[126:127], v[106:107], v[78:79], v[126:127]
	v_rcp_f32_e32 v134, v129
	v_fma_f32 v129, v135, s97, 1.0
	v_fma_f32 v135, v136, s97, 1.0
	v_pk_fma_f32 v[120:121], v[72:73], v[120:121], v[124:125]
	v_pk_fma_f32 v[122:123], v[74:75], v[122:123], v[126:127]
	v_mul_f32_e32 v135, v132, v135
	v_fma_f32 v136, v137, s97, 1.0
	v_pk_mul_f32 v[124:125], v[120:121], v[120:121]
	v_pk_mul_f32 v[126:127], v[122:123], v[122:123]
	v_mul_f32_e32 v129, v131, v129
	v_mul_f32_e32 v135, 0xc0135761, v135
	v_mul_f32_e32 v136, v133, v136
	v_fma_f32 v124, v124, s97, 1.0
	v_fma_f32 v125, v125, s97, 1.0
	v_fma_f32 v126, v126, s97, 1.0
	v_fma_f32 v127, v127, s97, 1.0
	v_mul_f32_e32 v129, 0xc0135761, v129
	v_exp_f32_e32 v135, v135
	v_mul_f32_e32 v136, 0xc0135761, v136
	v_mul_f32_e32 v124, v120, v124
	v_mul_f32_e32 v125, v121, v125
	v_mul_f32_e32 v126, v122, v126
	v_mul_f32_e32 v127, v123, v127
	v_exp_f32_e32 v129, v129
	v_exp_f32_e32 v137, v136
	v_mul_f32_e32 v124, 0xc0135761, v124
	v_mul_f32_e32 v125, 0xc0135761, v125
	v_mul_f32_e32 v126, 0xc0135761, v126
	v_mul_f32_e32 v127, 0xc0135761, v127
	v_exp_f32_e32 v124, v124
	v_exp_f32_e32 v125, v125
	v_exp_f32_e32 v126, v126
	v_exp_f32_e32 v127, v127
	v_add_f32_e32 v135, 1.0, v135
	v_add_f32_e32 v129, 1.0, v129
	v_rcp_f32_e32 v136, v135
	v_add_f32_e32 v135, 1.0, v137
	v_rcp_f32_e32 v137, v135
	v_rcp_f32_e32 v135, v129
	v_add_f32_e32 v124, 1.0, v124
	v_add_f32_e32 v125, 1.0, v125
	v_add_f32_e32 v126, 1.0, v126
	v_add_f32_e32 v127, 1.0, v127
	v_rcp_f32_e32 v124, v124
	v_rcp_f32_e32 v126, v126
	v_rcp_f32_e32 v127, v127
	v_rcp_f32_e32 v125, v125
	v_pk_mul_f32 v[130:131], v[130:131], v[134:135]
	v_ashrrev_i32_e32 v129, 31, v128
	v_pk_mul_f32 v[116:117], v[116:117], v[130:131]
	v_pk_mul_f32 v[122:123], v[122:123], v[126:127]
	v_pk_mul_f32 v[120:121], v[120:121], v[124:125]
	v_pk_mul_f32 v[122:123], v[114:115], v[122:123]
	v_pk_mul_f32 v[114:115], v[112:113], v[120:121]
	v_cvt_pk_bf16_f32 v112, v116, v117
	v_lshlrev_b64 v[116:117], 13, v[128:129]
	v_lshl_add_u64 v[116:117], s[44:45], 0, v[116:117]
	v_pk_mul_f32 v[132:133], v[132:133], v[136:137]
	v_lshl_add_u64 v[116:117], v[176:177], 1, v[116:117]
	v_pk_mul_f32 v[118:119], v[118:119], v[132:133]
	s_nop 0
	v_cvt_pk_bf16_f32 v113, v118, v119
	v_cvt_pk_bf16_f32 v114, v114, v115
	v_cvt_pk_bf16_f32 v115, v122, v123
	global_store_dwordx4 v[116:117], v[112:115], off nt

; __device__ __forceinline__ unsigned cvt_pk_bf16(float lo, float hi) { unsigned r; asm volatile("v_cvt_pk_bf16_f32 %0, %1, %2" : "=v"(r) : "v"(lo), "v"(hi)); return r; }
; __device__ __forceinline__ float dpp_ror1(float v) { return __builtin_bit_cast(float, __builtin_amdgcn_update_dpp(0, __builtin_bit_cast(int, v), 0x121, 0xf, 0xf, false)); }
; __device__ __forceinline__ float dpp_ror15(float v) { return __builtin_bit_cast(float, __builtin_amdgcn_update_dpp(0, __builtin_bit_cast(int, v), 0x12F, 0xf, 0xf, false)); }
;     __device__ __forceinline__ void operator()(const f32x4 (&acc)[2][2][4][2], const Unit& u, int wr, int wc, int fr, int fq) const {
;     ...
;                 const float fzp = zp ? 0.f : 1.f, fzn = zn ? 0.f : 1.f;
; #pragma unroll
;                 for (int n = 0; n < 2; ++n) {
;                     const f32x4 g = acc[ai][0][m][n], up = acc[ai][1][m][n];
;                     f32x4 tp = g, tn = g;
;                     if (!fix) { const f32x4 gm = (m > 0) ? acc[ai][0][m - 1][n] : acc[ai ^ 1][0][3][n], gx = (m < 3) ? acc[ai][0][m + 1][n] : acc[ai ^ 1][0][0][n];
;                         tp = (fr == 15) ? gm : g; tn = (fr == 0) ? gx : g; }
;                     f32x4 gp, gn;
; #pragma unroll
;                     for (int j = 0; j < 4; ++j) { gp[j] = dpp_ror1(tp[j]); gn[j] = dpp_ror15(tn[j]); }
;                     const f32x4 cv = (w0[n] * fzp) * gp + (w1[n] * g + ((w2[n] * fzn) * gn + bb[n]));
;                     const f32x4 inner = cv * (cv * cv * 0.044715f + 1.0f) * (-2.0f * 0.7978845608028654f * 1.4426950408889634f);
;                     f32x4 sg;
; #pragma unroll
;                     for (int j = 0; j < 4; ++j) sg[j] = __builtin_amdgcn_rcpf(1.0f + __builtin_amdgcn_exp2f(inner[j]));
;                     res[n] = cv * sg * up;
;                 }
;                 if (valid) { u32x4 w; w.x = cvt_pk_bf16(res[0][0], res[0][1]); w.y = cvt_pk_bf16(res[0][2], res[0][3]); w.z = cvt_pk_bf16(res[1][0], res[1][1]); w.w = cvt_pk_bf16(res[1][2], res[1][3]);
;                     __builtin_nontemporal_store(w, (u32x4*)(ACT + (size_t)grow * 4096 + ch0)); }
.LBB0_661:
	v_cndmask_b32_e64 v111, v63, v111, s[16:17]
	v_cndmask_b32_e64 v119, v60, v44, s[18:19]
	v_mov_b32_e32 v122, 0
	v_mov_b32_dpp v121, v111 row_ror:1 row_mask:0xf bank_mask:0xf
	v_cndmask_b32_e64 v111, v59, v107, s[16:17]
	v_cndmask_b32_e64 v107, v58, v106, s[16:17]
	v_cndmask_b32_e64 v106, v57, v105, s[16:17]
	v_cndmask_b32_e64 v105, v56, v104, s[16:17]
	v_cndmask_b32_e64 v109, v61, v109, s[16:17]
	v_cndmask_b32_e64 v108, v60, v108, s[16:17]
	v_mov_b32_dpp v122, v119 row_ror:15 row_mask:0xf bank_mask:0xf
	v_mov_b32_dpp v104, v105 row_ror:1 row_mask:0xf bank_mask:0xf
	v_cndmask_b32_e64 v110, v62, v110, s[16:17]
	v_mov_b32_dpp v118, v108 row_ror:1 row_mask:0xf bank_mask:0xf
	v_mov_b32_dpp v119, v109 row_ror:1 row_mask:0xf bank_mask:0xf
	v_cndmask_b32_e64 v109, v56, v40, s[18:19]
	v_mov_b32_dpp v105, v106 row_ror:1 row_mask:0xf bank_mask:0xf
	v_cndmask_b32_e64 v113, v63, v47, s[18:19]
	v_cndmask_b32_e64 v115, v62, v46, s[18:19]
	v_mov_b32_dpp v120, v110 row_ror:1 row_mask:0xf bank_mask:0xf
	v_cndmask_b32_e64 v110, v57, v41, s[18:19]
	v_mov_b32_dpp v108, v109 row_ror:15 row_mask:0xf bank_mask:0xf
	v_mov_b32_dpp v106, v107 row_ror:1 row_mask:0xf bank_mask:0xf
	v_cndmask_b32_e64 v117, v61, v45, s[18:19]
	v_mov_b32_dpp v124, v115 row_ror:15 row_mask:0xf bank_mask:0xf
	v_mov_b32_dpp v125, v113 row_ror:15 row_mask:0xf bank_mask:0xf
	v_cndmask_b32_e64 v113, v59, v43, s[18:19]
	v_cndmask_b32_e64 v115, v58, v42, s[18:19]
	v_mov_b32_dpp v109, v110 row_ror:15 row_mask:0xf bank_mask:0xf
	v_mov_b32_dpp v107, v111 row_ror:1 row_mask:0xf bank_mask:0xf
	v_mov_b32_dpp v123, v117 row_ror:15 row_mask:0xf bank_mask:0xf
	v_mov_b32_dpp v110, v115 row_ror:15 row_mask:0xf bank_mask:0xf
	v_mov_b32_dpp v111, v113 row_ror:15 row_mask:0xf bank_mask:0xf
	s_and_saveexec_b64 s[80:81], s[82:83]
	s_cbranch_execz .LBB0_663
	s_waitcnt vmcnt(0)
	v_pk_mul_f32 v[132:133], v[96:97], v[114:115] op_sel_hi:[1,0]
	v_pk_mul_f32 v[128:129], v[88:89], v[116:117] op_sel_hi:[1,0]
	v_pk_fma_f32 v[122:123], v[132:133], v[122:123], v[100:101]
	v_pk_mul_f32 v[130:131], v[98:99], v[114:115] op_sel_hi:[1,0]
	v_pk_fma_f32 v[122:123], v[60:61], v[92:93], v[122:123]
	v_pk_fma_f32 v[124:125], v[130:131], v[124:125], v[102:103]
	v_pk_fma_f32 v[118:119], v[128:129], v[118:119], v[122:123]
	v_pk_mul_f32 v[126:127], v[90:91], v[116:117] op_sel_hi:[1,0]
	v_pk_mul_f32 v[122:123], v[118:119], v[118:119]
	v_pk_fma_f32 v[124:125], v[62:63], v[94:95], v[124:125]
	v_fma_f32 v113, v122, s97, 1.0
	v_mul_f32_e32 v113, v118, v113
	v_mul_f32_e32 v113, 0xc0135761, v113
	v_exp_f32_e32 v113, v113
	v_pk_fma_f32 v[120:121], v[126:127], v[120:121], v[124:125]
	v_add_f32_e32 v113, 1.0, v113
	v_pk_mul_f32 v[124:125], v[120:121], v[120:121]
	v_rcp_f32_e32 v122, v113
	v_fma_f32 v115, v124, s97, 1.0
	v_mul_f32_e32 v115, v120, v115
	v_fma_f32 v117, v125, s97, 1.0
	v_mul_f32_e32 v115, 0xc0135761, v115
	v_mul_f32_e32 v117, v121, v117
	v_fma_f32 v113, v123, s97, 1.0
	v_exp_f32_e32 v115, v115
	v_mul_f32_e32 v117, 0xc0135761, v117
	v_mul_f32_e32 v113, v119, v113
	v_exp_f32_e32 v117, v117
	v_mul_f32_e32 v113, 0xc0135761, v113
	v_exp_f32_e32 v113, v113
	v_add_f32_e32 v115, 1.0, v115
	v_rcp_f32_e32 v124, v115
	v_add_f32_e32 v115, 1.0, v117
	v_rcp_f32_e32 v125, v115
	v_add_f32_e32 v113, 1.0, v113
	v_rcp_f32_e32 v123, v113
	v_ashrrev_i32_e32 v113, 31, v112
	v_pk_mul_f32 v[120:121], v[120:121], v[124:125]
	v_pk_mul_f32 v[124:125], v[82:83], v[114:115] op_sel_hi:[1,0]
	v_pk_mul_f32 v[114:115], v[80:81], v[114:115] op_sel_hi:[1,0]
	v_pk_fma_f32 v[110:111], v[124:125], v[110:111], v[86:87]
	v_pk_fma_f32 v[108:109], v[114:115], v[108:109], v[84:85]
	v_pk_mul_f32 v[118:119], v[118:119], v[122:123]
	v_pk_mul_f32 v[122:123], v[74:75], v[116:117] op_sel_hi:[1,0]
	v_pk_mul_f32 v[116:117], v[72:73], v[116:117] op_sel_hi:[1,0]
	v_pk_fma_f32 v[108:109], v[56:57], v[76:77], v[108:109]
	v_pk_fma_f32 v[110:111], v[58:59], v[78:79], v[110:111]
	v_pk_fma_f32 v[104:105], v[116:117], v[104:105], v[108:109]
	v_pk_fma_f32 v[106:107], v[122:123], v[106:107], v[110:111]
	v_pk_mul_f32 v[108:109], v[104:105], v[104:105]
	v_pk_mul_f32 v[110:111], v[106:107], v[106:107]
	v_fma_f32 v108, v108, s97, 1.0
	v_fma_f32 v109, v109, s97, 1.0
	v_fma_f32 v110, v110, s97, 1.0
	v_fma_f32 v111, v111, s97, 1.0
	v_mul_f32_e32 v108, v104, v108
	v_mul_f32_e32 v109, v105, v109
	v_mul_f32_e32 v110, v106, v110
	v_mul_f32_e32 v111, v107, v111
	v_mul_f32_e32 v108, 0xc0135761, v108
	v_mul_f32_e32 v109, 0xc0135761, v109
	v_mul_f32_e32 v110, 0xc0135761, v110
	v_mul_f32_e32 v111, 0xc0135761, v111
	v_exp_f32_e32 v108, v108
	v_exp_f32_e32 v109, v109
	v_exp_f32_e32 v110, v110
	v_exp_f32_e32 v111, v111
	v_add_f32_e32 v108, 1.0, v108
	v_add_f32_e32 v109, 1.0, v109
	v_add_f32_e32 v110, 1.0, v110
	v_add_f32_e32 v111, 1.0, v111
	v_rcp_f32_e32 v108, v108
	v_rcp_f32_e32 v110, v110
	v_rcp_f32_e32 v111, v111
	v_rcp_f32_e32 v109, v109
	v_pk_mul_f32 v[68:69], v[68:69], v[118:119]
	v_pk_mul_f32 v[70:71], v[70:71], v[120:121]
	v_pk_mul_f32 v[106:107], v[106:107], v[110:111]
	v_pk_mul_f32 v[104:105], v[104:105], v[108:109]
	v_pk_mul_f32 v[106:107], v[66:67], v[106:107]
	v_pk_mul_f32 v[66:67], v[64:65], v[104:105]
	v_cvt_pk_bf16_f32 v64, v68, v69
	v_lshlrev_b64 v[68:69], 13, v[112:113]
	v_lshl_add_u64 v[68:69], s[44:45], 0, v[68:69]
	v_lshl_add_u64 v[68:69], v[176:177], 1, v[68:69]
	v_cvt_pk_bf16_f32 v65, v70, v71
	v_cvt_pk_bf16_f32 v66, v66, v67
	v_cvt_pk_bf16_f32 v67, v106, v107
	global_store_dwordx4 v[68:69], v[64:67], off nt

; __device__ __forceinline__ unsigned cvt_pk_bf16(float lo, float hi) { unsigned r; asm volatile("v_cvt_pk_bf16_f32 %0, %1, %2" : "=v"(r) : "v"(lo), "v"(hi)); return r; }
; __device__ __forceinline__ float dpp_ror1(float v) { return __builtin_bit_cast(float, __builtin_amdgcn_update_dpp(0, __builtin_bit_cast(int, v), 0x121, 0xf, 0xf, false)); }
; __device__ __forceinline__ float dpp_ror15(float v) { return __builtin_bit_cast(float, __builtin_amdgcn_update_dpp(0, __builtin_bit_cast(int, v), 0x12F, 0xf, 0xf, false)); }
;     __device__ __forceinline__ void operator()(const f32x4 (&acc)[2][2][4][2], const Unit& u, int wr, int wc, int fr, int fq) const {
;     ...
;                 const float fzp = zp ? 0.f : 1.f, fzn = zn ? 0.f : 1.f;
; #pragma unroll
;                 for (int n = 0; n < 2; ++n) {
;                     const f32x4 g = acc[ai][0][m][n], up = acc[ai][1][m][n];
;                     f32x4 tp = g, tn = g;
;                     if (!fix) { const f32x4 gm = (m > 0) ? acc[ai][0][m - 1][n] : acc[ai ^ 1][0][3][n], gx = (m < 3) ? acc[ai][0][m + 1][n] : acc[ai ^ 1][0][0][n];
;                         tp = (fr == 15) ? gm : g; tn = (fr == 0) ? gx : g; }
;                     f32x4 gp, gn;
; #pragma unroll
;                     for (int j = 0; j < 4; ++j) { gp[j] = dpp_ror1(tp[j]); gn[j] = dpp_ror15(tn[j]); }
;                     const f32x4 cv = (w0[n] * fzp) * gp + (w1[n] * g + ((w2[n] * fzn) * gn + bb[n]));
;                     const f32x4 inner = cv * (cv * cv * 0.044715f + 1.0f) * (-2.0f * 0.7978845608028654f * 1.4426950408889634f);
;                     f32x4 sg;
; #pragma unroll
;                     for (int j = 0; j < 4; ++j) sg[j] = __builtin_amdgcn_rcpf(1.0f + __builtin_amdgcn_exp2f(inner[j]));
;                     res[n] = cv * sg * up;
;                 }
;                 if (valid) { u32x4 w; w.x = cvt_pk_bf16(res[0][0], res[0][1]); w.y = cvt_pk_bf16(res[0][2], res[0][3]); w.z = cvt_pk_bf16(res[1][0], res[1][1]); w.w = cvt_pk_bf16(res[1][2], res[1][3]);
;                     __builtin_nontemporal_store(w, (u32x4*)(ACT + (size_t)grow * 4096 + ch0)); }
.LBB0_669:
	v_cndmask_b32_e64 v69, v46, v22, s[18:19]
	v_cndmask_b32_e64 v63, v47, v63, s[16:17]
	v_cndmask_b32_e64 v67, v44, v20, s[18:19]
	v_mov_b32_dpp v104, v69 row_ror:15 row_mask:0xf bank_mask:0xf
	v_cndmask_b32_e64 v61, v45, v61, s[16:17]
	v_mov_b32_dpp v69, v63 row_ror:1 row_mask:0xf bank_mask:0xf
	v_cndmask_b32_e64 v63, v43, v59, s[16:17]
	v_cndmask_b32_e64 v59, v42, v58, s[16:17]
	v_cndmask_b32_e64 v58, v41, v57, s[16:17]
	v_cndmask_b32_e64 v57, v40, v56, s[16:17]
	v_cndmask_b32_e64 v60, v44, v60, s[16:17]
	v_cndmask_b32_e64 v68, v45, v21, s[18:19]
	v_mov_b32_dpp v70, v67 row_ror:15 row_mask:0xf bank_mask:0xf
	v_mov_b32_dpp v56, v57 row_ror:1 row_mask:0xf bank_mask:0xf
	v_cndmask_b32_e64 v62, v46, v62, s[16:17]
	v_mov_b32_dpp v66, v60 row_ror:1 row_mask:0xf bank_mask:0xf
	v_mov_b32_dpp v67, v61 row_ror:1 row_mask:0xf bank_mask:0xf
	v_mov_b32_dpp v71, v68 row_ror:15 row_mask:0xf bank_mask:0xf
	v_cndmask_b32_e64 v61, v40, v16, s[18:19]
	v_mov_b32_dpp v57, v58 row_ror:1 row_mask:0xf bank_mask:0xf
	v_cndmask_b32_e64 v65, v47, v23, s[18:19]
	v_mov_b32_dpp v68, v62 row_ror:1 row_mask:0xf bank_mask:0xf
	v_cndmask_b32_e64 v62, v41, v17, s[18:19]
	v_mov_b32_dpp v60, v61 row_ror:15 row_mask:0xf bank_mask:0xf
	v_mov_b32_dpp v58, v59 row_ror:1 row_mask:0xf bank_mask:0xf
	v_mov_b32_dpp v105, v65 row_ror:15 row_mask:0xf bank_mask:0xf
	v_cndmask_b32_e64 v65, v43, v19, s[18:19]
	v_cndmask_b32_e64 v107, v42, v18, s[18:19]
	v_mov_b32_dpp v61, v62 row_ror:15 row_mask:0xf bank_mask:0xf
	v_mov_b32_dpp v59, v63 row_ror:1 row_mask:0xf bank_mask:0xf
	v_mov_b32_dpp v62, v107 row_ror:15 row_mask:0xf bank_mask:0xf
	s_nop 0
	v_mov_b32_dpp v63, v65 row_ror:15 row_mask:0xf bank_mask:0xf
	s_and_saveexec_b64 s[64:65], s[80:81]
	s_cbranch_execz .LBB0_671
	s_waitcnt vmcnt(0)
	v_pk_fma_f32 v[70:71], v[96:97], v[70:71], v[100:101]
	v_pk_fma_f32 v[104:105], v[98:99], v[104:105], v[102:103]
	v_pk_fma_f32 v[70:71], v[44:45], v[92:93], v[70:71]
	v_pk_fma_f32 v[104:105], v[46:47], v[94:95], v[104:105]
	v_pk_fma_f32 v[66:67], v[88:89], v[66:67], v[70:71]
	v_pk_fma_f32 v[68:69], v[90:91], v[68:69], v[104:105]
	v_pk_mul_f32 v[70:71], v[66:67], v[66:67]
	v_pk_fma_f32 v[62:63], v[82:83], v[62:63], v[86:87]
	v_fma_f32 v65, v70, s97, 1.0
	v_mul_f32_e32 v65, v66, v65
	v_mul_f32_e32 v65, 0xc0135761, v65
	v_exp_f32_e32 v65, v65
	v_pk_fma_f32 v[60:61], v[80:81], v[60:61], v[84:85]
	v_pk_mul_f32 v[104:105], v[68:69], v[68:69]
	v_pk_fma_f32 v[60:61], v[40:41], v[76:77], v[60:61]
	v_add_f32_e32 v65, 1.0, v65
	v_pk_fma_f32 v[62:63], v[42:43], v[78:79], v[62:63]
	v_rcp_f32_e32 v70, v65
	v_fma_f32 v65, v71, s97, 1.0
	v_fma_f32 v71, v104, s97, 1.0
	v_pk_fma_f32 v[56:57], v[72:73], v[56:57], v[60:61]
	v_pk_fma_f32 v[58:59], v[74:75], v[58:59], v[62:63]
	v_mul_f32_e32 v71, v68, v71
	v_fma_f32 v104, v105, s97, 1.0
	v_pk_mul_f32 v[60:61], v[56:57], v[56:57]
	v_pk_mul_f32 v[62:63], v[58:59], v[58:59]
	v_mul_f32_e32 v65, v67, v65
	v_mul_f32_e32 v71, 0xc0135761, v71
	v_mul_f32_e32 v104, v69, v104
	v_fma_f32 v60, v60, s97, 1.0
	v_fma_f32 v61, v61, s97, 1.0
	v_fma_f32 v62, v62, s97, 1.0
	v_fma_f32 v63, v63, s97, 1.0
	v_mul_f32_e32 v65, 0xc0135761, v65
	v_exp_f32_e32 v71, v71
	v_mul_f32_e32 v104, 0xc0135761, v104
	v_mul_f32_e32 v60, v56, v60
	v_mul_f32_e32 v61, v57, v61
	v_mul_f32_e32 v62, v58, v62
	v_mul_f32_e32 v63, v59, v63
	v_exp_f32_e32 v65, v65
	v_exp_f32_e32 v105, v104
	v_mul_f32_e32 v60, 0xc0135761, v60
	v_mul_f32_e32 v61, 0xc0135761, v61
	v_mul_f32_e32 v62, 0xc0135761, v62
	v_mul_f32_e32 v63, 0xc0135761, v63
	v_exp_f32_e32 v60, v60
	v_exp_f32_e32 v61, v61
	v_exp_f32_e32 v62, v62
	v_exp_f32_e32 v63, v63
	v_add_f32_e32 v71, 1.0, v71
	v_add_f32_e32 v65, 1.0, v65
	v_rcp_f32_e32 v104, v71
	v_add_f32_e32 v71, 1.0, v105
	v_rcp_f32_e32 v105, v71
	v_rcp_f32_e32 v71, v65
	v_add_f32_e32 v60, 1.0, v60
	v_add_f32_e32 v61, 1.0, v61
	v_add_f32_e32 v62, 1.0, v62
	v_add_f32_e32 v63, 1.0, v63
	v_rcp_f32_e32 v60, v60
	v_rcp_f32_e32 v62, v62
	v_rcp_f32_e32 v63, v63
	v_rcp_f32_e32 v61, v61
	v_pk_mul_f32 v[66:67], v[66:67], v[70:71]
	v_ashrrev_i32_e32 v65, 31, v64
	v_pk_mul_f32 v[52:53], v[52:53], v[66:67]
	v_pk_mul_f32 v[58:59], v[58:59], v[62:63]
	v_pk_mul_f32 v[56:57], v[56:57], v[60:61]
	v_pk_mul_f32 v[58:59], v[50:51], v[58:59]
	v_pk_mul_f32 v[50:51], v[48:49], v[56:57]
	v_cvt_pk_bf16_f32 v48, v52, v53
	v_lshlrev_b64 v[52:53], 13, v[64:65]
	v_lshl_add_u64 v[52:53], s[44:45], 0, v[52:53]
	v_pk_mul_f32 v[68:69], v[68:69], v[104:105]
	v_lshl_add_u64 v[52:53], v[176:177], 1, v[52:53]
	v_pk_mul_f32 v[54:55], v[54:55], v[68:69]
	s_nop 0
	v_cvt_pk_bf16_f32 v49, v54, v55
	v_cvt_pk_bf16_f32 v50, v50, v51
	v_cvt_pk_bf16_f32 v51, v58, v59
	global_store_dwordx4 v[52:53], v[48:51], off nt

; __device__ __forceinline__ unsigned cvt_pk_bf16(float lo, float hi) { unsigned r; asm volatile("v_cvt_pk_bf16_f32 %0, %1, %2" : "=v"(r) : "v"(lo), "v"(hi)); return r; }
; __device__ __forceinline__ float dpp_ror1(float v) { return __builtin_bit_cast(float, __builtin_amdgcn_update_dpp(0, __builtin_bit_cast(int, v), 0x121, 0xf, 0xf, false)); }
; __device__ __forceinline__ float dpp_ror15(float v) { return __builtin_bit_cast(float, __builtin_amdgcn_update_dpp(0, __builtin_bit_cast(int, v), 0x12F, 0xf, 0xf, false)); }
;     __device__ __forceinline__ void operator()(const f32x4 (&acc)[2][2][4][2], const Unit& u, int wr, int wc, int fr, int fq) const {
;     ...
;                 const float fzp = zp ? 0.f : 1.f, fzn = zn ? 0.f : 1.f;
; #pragma unroll
;                 for (int n = 0; n < 2; ++n) {
;                     const f32x4 g = acc[ai][0][m][n], up = acc[ai][1][m][n];
;                     f32x4 tp = g, tn = g;
;                     if (!fix) { const f32x4 gm = (m > 0) ? acc[ai][0][m - 1][n] : acc[ai ^ 1][0][3][n], gx = (m < 3) ? acc[ai][0][m + 1][n] : acc[ai ^ 1][0][0][n];
;                         tp = (fr == 15) ? gm : g; tn = (fr == 0) ? gx : g; }
;                     f32x4 gp, gn;
; #pragma unroll
;                     for (int j = 0; j < 4; ++j) { gp[j] = dpp_ror1(tp[j]); gn[j] = dpp_ror15(tn[j]); }
;                     const f32x4 cv = (w0[n] * fzp) * gp + (w1[n] * g + ((w2[n] * fzn) * gn + bb[n]));
;                     const f32x4 inner = cv * (cv * cv * 0.044715f + 1.0f) * (-2.0f * 0.7978845608028654f * 1.4426950408889634f);
;                     f32x4 sg;
; #pragma unroll
;                     for (int j = 0; j < 4; ++j) sg[j] = __builtin_amdgcn_rcpf(1.0f + __builtin_amdgcn_exp2f(inner[j]));
;                     res[n] = cv * sg * up;
;                 }
;                 if (valid) { u32x4 w; w.x = cvt_pk_bf16(res[0][0], res[0][1]); w.y = cvt_pk_bf16(res[0][2], res[0][3]); w.z = cvt_pk_bf16(res[1][0], res[1][1]); w.w = cvt_pk_bf16(res[1][2], res[1][3]);
;                     __builtin_nontemporal_store(w, (u32x4*)(ACT + (size_t)grow * 4096 + ch0)); }
.LBB0_677:
	v_cndmask_b32_e64 v53, v22, v14, s[18:19]
	v_cndmask_b32_e64 v47, v23, v47, s[16:17]
	v_cndmask_b32_e64 v51, v20, v12, s[18:19]
	v_mov_b32_dpp v56, v53 row_ror:15 row_mask:0xf bank_mask:0xf
	v_cndmask_b32_e64 v45, v21, v45, s[16:17]
	v_mov_b32_dpp v53, v47 row_ror:1 row_mask:0xf bank_mask:0xf
	v_cndmask_b32_e64 v47, v19, v43, s[16:17]
	v_cndmask_b32_e64 v43, v18, v42, s[16:17]
	v_cndmask_b32_e64 v42, v17, v41, s[16:17]
	v_cndmask_b32_e64 v41, v16, v40, s[16:17]
	v_cndmask_b32_e64 v44, v20, v44, s[16:17]
	v_cndmask_b32_e64 v52, v21, v13, s[18:19]
	v_mov_b32_dpp v54, v51 row_ror:15 row_mask:0xf bank_mask:0xf
	v_mov_b32_dpp v40, v41 row_ror:1 row_mask:0xf bank_mask:0xf
	v_cndmask_b32_e64 v46, v22, v46, s[16:17]
	v_mov_b32_dpp v50, v44 row_ror:1 row_mask:0xf bank_mask:0xf
	v_mov_b32_dpp v51, v45 row_ror:1 row_mask:0xf bank_mask:0xf
	v_mov_b32_dpp v55, v52 row_ror:15 row_mask:0xf bank_mask:0xf
	v_cndmask_b32_e64 v45, v16, v8, s[18:19]
	v_mov_b32_dpp v41, v42 row_ror:1 row_mask:0xf bank_mask:0xf
	v_cndmask_b32_e64 v49, v23, v15, s[18:19]
	v_mov_b32_dpp v52, v46 row_ror:1 row_mask:0xf bank_mask:0xf
	v_cndmask_b32_e64 v46, v17, v9, s[18:19]
	v_mov_b32_dpp v44, v45 row_ror:15 row_mask:0xf bank_mask:0xf
	v_mov_b32_dpp v42, v43 row_ror:1 row_mask:0xf bank_mask:0xf
	v_mov_b32_dpp v57, v49 row_ror:15 row_mask:0xf bank_mask:0xf
	v_cndmask_b32_e64 v49, v19, v11, s[18:19]
	v_cndmask_b32_e64 v58, v18, v10, s[18:19]
	v_mov_b32_dpp v45, v46 row_ror:15 row_mask:0xf bank_mask:0xf
	v_mov_b32_dpp v43, v47 row_ror:1 row_mask:0xf bank_mask:0xf
	v_mov_b32_dpp v46, v58 row_ror:15 row_mask:0xf bank_mask:0xf
	s_nop 0
	v_mov_b32_dpp v47, v49 row_ror:15 row_mask:0xf bank_mask:0xf
	s_and_saveexec_b64 s[64:65], s[80:81]
	s_cbranch_execz .LBB0_679
	s_waitcnt vmcnt(0)
	v_pk_fma_f32 v[54:55], v[96:97], v[54:55], v[100:101]
	v_pk_fma_f32 v[56:57], v[98:99], v[56:57], v[102:103]
	v_pk_fma_f32 v[54:55], v[20:21], v[92:93], v[54:55]
	v_pk_fma_f32 v[56:57], v[22:23], v[94:95], v[56:57]
	v_pk_fma_f32 v[50:51], v[88:89], v[50:51], v[54:55]
	v_pk_fma_f32 v[52:53], v[90:91], v[52:53], v[56:57]
	v_pk_mul_f32 v[54:55], v[50:51], v[50:51]
	v_pk_fma_f32 v[46:47], v[82:83], v[46:47], v[86:87]
	v_fma_f32 v49, v54, s97, 1.0
	v_mul_f32_e32 v49, v50, v49
	v_mul_f32_e32 v49, 0xc0135761, v49
	v_exp_f32_e32 v49, v49
	v_pk_fma_f32 v[44:45], v[80:81], v[44:45], v[84:85]
	v_pk_mul_f32 v[56:57], v[52:53], v[52:53]
	v_pk_fma_f32 v[44:45], v[16:17], v[76:77], v[44:45]
	v_add_f32_e32 v49, 1.0, v49
	v_pk_fma_f32 v[46:47], v[18:19], v[78:79], v[46:47]
	v_rcp_f32_e32 v54, v49
	v_fma_f32 v49, v55, s97, 1.0
	v_fma_f32 v55, v56, s97, 1.0
	v_pk_fma_f32 v[40:41], v[72:73], v[40:41], v[44:45]
	v_pk_fma_f32 v[42:43], v[74:75], v[42:43], v[46:47]
	v_mul_f32_e32 v55, v52, v55
	v_fma_f32 v56, v57, s97, 1.0
	v_pk_mul_f32 v[44:45], v[40:41], v[40:41]
	v_pk_mul_f32 v[46:47], v[42:43], v[42:43]
	v_mul_f32_e32 v49, v51, v49
	v_mul_f32_e32 v55, 0xc0135761, v55
	v_mul_f32_e32 v56, v53, v56
	v_fma_f32 v44, v44, s97, 1.0
	v_fma_f32 v45, v45, s97, 1.0
	v_fma_f32 v46, v46, s97, 1.0
	v_fma_f32 v47, v47, s97, 1.0
	v_mul_f32_e32 v49, 0xc0135761, v49
	v_exp_f32_e32 v55, v55
	v_mul_f32_e32 v56, 0xc0135761, v56
	v_mul_f32_e32 v44, v40, v44
	v_mul_f32_e32 v45, v41, v45
	v_mul_f32_e32 v46, v42, v46
	v_mul_f32_e32 v47, v43, v47
	v_exp_f32_e32 v49, v49
	v_exp_f32_e32 v57, v56
	v_mul_f32_e32 v44, 0xc0135761, v44
	v_mul_f32_e32 v45, 0xc0135761, v45
	v_mul_f32_e32 v46, 0xc0135761, v46
	v_mul_f32_e32 v47, 0xc0135761, v47
	v_exp_f32_e32 v44, v44
	v_exp_f32_e32 v45, v45
	v_exp_f32_e32 v46, v46
	v_exp_f32_e32 v47, v47
	v_add_f32_e32 v55, 1.0, v55
	v_add_f32_e32 v49, 1.0, v49
	v_rcp_f32_e32 v56, v55
	v_add_f32_e32 v55, 1.0, v57
	v_rcp_f32_e32 v57, v55
	v_rcp_f32_e32 v55, v49
	v_add_f32_e32 v44, 1.0, v44
	v_add_f32_e32 v45, 1.0, v45
	v_add_f32_e32 v46, 1.0, v46
	v_add_f32_e32 v47, 1.0, v47
	v_rcp_f32_e32 v44, v44
	v_rcp_f32_e32 v46, v46
	v_rcp_f32_e32 v47, v47
	v_rcp_f32_e32 v45, v45
	v_pk_mul_f32 v[50:51], v[50:51], v[54:55]
	v_ashrrev_i32_e32 v49, 31, v48
	v_pk_mul_f32 v[32:33], v[32:33], v[50:51]
	v_pk_mul_f32 v[42:43], v[42:43], v[46:47]
	v_pk_mul_f32 v[40:41], v[40:41], v[44:45]
	v_pk_mul_f32 v[42:43], v[26:27], v[42:43]
	v_pk_mul_f32 v[26:27], v[24:25], v[40:41]
	v_cvt_pk_bf16_f32 v24, v32, v33
	v_lshlrev_b64 v[32:33], 13, v[48:49]
	v_lshl_add_u64 v[32:33], s[44:45], 0, v[32:33]
	v_pk_mul_f32 v[52:53], v[52:53], v[56:57]
	v_lshl_add_u64 v[32:33], v[176:177], 1, v[32:33]
	v_pk_mul_f32 v[34:35], v[34:35], v[52:53]
	s_nop 0
	v_cvt_pk_bf16_f32 v25, v34, v35
	v_cvt_pk_bf16_f32 v26, v26, v27
	v_cvt_pk_bf16_f32 v27, v42, v43
	global_store_dwordx4 v[32:33], v[24:27], off nt

; __device__ __forceinline__ unsigned cvt_pk_bf16(float lo, float hi) { unsigned r; asm volatile("v_cvt_pk_bf16_f32 %0, %1, %2" : "=v"(r) : "v"(lo), "v"(hi)); return r; }
; __device__ __forceinline__ float dpp_ror1(float v) { return __builtin_bit_cast(float, __builtin_amdgcn_update_dpp(0, __builtin_bit_cast(int, v), 0x121, 0xf, 0xf, false)); }
; __device__ __forceinline__ float dpp_ror15(float v) { return __builtin_bit_cast(float, __builtin_amdgcn_update_dpp(0, __builtin_bit_cast(int, v), 0x12F, 0xf, 0xf, false)); }
;     __device__ __forceinline__ void operator()(const f32x4 (&acc)[2][2][4][2], const Unit& u, int wr, int wc, int fr, int fq) const {
;     ...
;                 const float fzp = zp ? 0.f : 1.f, fzn = zn ? 0.f : 1.f;
; #pragma unroll
;                 for (int n = 0; n < 2; ++n) {
;                     const f32x4 g = acc[ai][0][m][n], up = acc[ai][1][m][n];
;                     f32x4 tp = g, tn = g;
;                     if (!fix) { const f32x4 gm = (m > 0) ? acc[ai][0][m - 1][n] : acc[ai ^ 1][0][3][n], gx = (m < 3) ? acc[ai][0][m + 1][n] : acc[ai ^ 1][0][0][n];
;                         tp = (fr == 15) ? gm : g; tn = (fr == 0) ? gx : g; }
;                     f32x4 gp, gn;
; #pragma unroll
;                     for (int j = 0; j < 4; ++j) { gp[j] = dpp_ror1(tp[j]); gn[j] = dpp_ror15(tn[j]); }
;                     const f32x4 cv = (w0[n] * fzp) * gp + (w1[n] * g + ((w2[n] * fzn) * gn + bb[n]));
;                     const f32x4 inner = cv * (cv * cv * 0.044715f + 1.0f) * (-2.0f * 0.7978845608028654f * 1.4426950408889634f);
;                     f32x4 sg;
; #pragma unroll
;                     for (int j = 0; j < 4; ++j) sg[j] = __builtin_amdgcn_rcpf(1.0f + __builtin_amdgcn_exp2f(inner[j]));
;                     res[n] = cv * sg * up;
;                 }
;                 if (valid) { u32x4 w; w.x = cvt_pk_bf16(res[0][0], res[0][1]); w.y = cvt_pk_bf16(res[0][2], res[0][3]); w.z = cvt_pk_bf16(res[1][0], res[1][1]); w.w = cvt_pk_bf16(res[1][2], res[1][3]);
;                     __builtin_nontemporal_store(w, (u32x4*)(ACT + (size_t)grow * 4096 + ch0)); }
.LBB0_685:
	v_cndmask_b32_e64 v33, v14, v38, s[18:19]
	v_cndmask_b32_e64 v27, v12, v36, s[18:19]
	v_cndmask_b32_e64 v23, v15, v23, s[16:17]
	v_mov_b32_dpp v36, v33 row_ror:15 row_mask:0xf bank_mask:0xf
	v_cndmask_b32_e64 v21, v13, v21, s[16:17]
	v_cndmask_b32_e64 v20, v12, v20, s[16:17]
	v_mov_b32_dpp v33, v23 row_ror:1 row_mask:0xf bank_mask:0xf
	v_cndmask_b32_e64 v23, v11, v19, s[16:17]
	v_cndmask_b32_e64 v19, v10, v18, s[16:17]
	v_cndmask_b32_e64 v18, v9, v17, s[16:17]
	v_cndmask_b32_e64 v17, v8, v16, s[16:17]
	v_cndmask_b32_e64 v32, v13, v37, s[18:19]
	v_mov_b32_dpp v34, v27 row_ror:15 row_mask:0xf bank_mask:0xf
	v_mov_b32_dpp v16, v17 row_ror:1 row_mask:0xf bank_mask:0xf
	v_cndmask_b32_e64 v22, v14, v22, s[16:17]
	v_mov_b32_dpp v26, v20 row_ror:1 row_mask:0xf bank_mask:0xf
	v_mov_b32_dpp v27, v21 row_ror:1 row_mask:0xf bank_mask:0xf
	v_mov_b32_dpp v35, v32 row_ror:15 row_mask:0xf bank_mask:0xf
	v_cndmask_b32_e64 v21, v8, v28, s[18:19]
	v_mov_b32_dpp v17, v18 row_ror:1 row_mask:0xf bank_mask:0xf
	v_cndmask_b32_e64 v25, v15, v39, s[18:19]
	v_mov_b32_dpp v32, v22 row_ror:1 row_mask:0xf bank_mask:0xf
	v_cndmask_b32_e64 v22, v9, v29, s[18:19]
	v_mov_b32_dpp v20, v21 row_ror:15 row_mask:0xf bank_mask:0xf
	v_mov_b32_dpp v18, v19 row_ror:1 row_mask:0xf bank_mask:0xf
	v_mov_b32_dpp v37, v25 row_ror:15 row_mask:0xf bank_mask:0xf
	v_cndmask_b32_e64 v25, v11, v31, s[18:19]
	v_cndmask_b32_e64 v30, v10, v30, s[18:19]
	v_mov_b32_dpp v21, v22 row_ror:15 row_mask:0xf bank_mask:0xf
	v_mov_b32_dpp v19, v23 row_ror:1 row_mask:0xf bank_mask:0xf
	v_mov_b32_dpp v22, v30 row_ror:15 row_mask:0xf bank_mask:0xf
	s_nop 0
	v_mov_b32_dpp v23, v25 row_ror:15 row_mask:0xf bank_mask:0xf
	s_and_saveexec_b64 s[16:17], s[20:21]
	s_cbranch_execz .LBB0_687
	s_waitcnt vmcnt(0)
	v_pk_fma_f32 v[30:31], v[96:97], v[34:35], v[100:101]
	v_pk_fma_f32 v[28:29], v[98:99], v[36:37], v[102:103]
	v_pk_fma_f32 v[12:13], v[12:13], v[92:93], v[30:31]
	v_pk_fma_f32 v[14:15], v[14:15], v[94:95], v[28:29]
	v_pk_fma_f32 v[12:13], v[88:89], v[26:27], v[12:13]
	v_pk_fma_f32 v[14:15], v[90:91], v[32:33], v[14:15]
	v_pk_mul_f32 v[26:27], v[12:13], v[12:13]
	v_pk_fma_f32 v[22:23], v[82:83], v[22:23], v[86:87]
	v_fma_f32 v25, v26, s97, 1.0
	v_mul_f32_e32 v25, v12, v25
	v_mul_f32_e32 v25, 0xc0135761, v25
	v_exp_f32_e32 v25, v25
	v_pk_fma_f32 v[20:21], v[80:81], v[20:21], v[84:85]
	v_pk_mul_f32 v[28:29], v[14:15], v[14:15]
	v_pk_fma_f32 v[8:9], v[8:9], v[76:77], v[20:21]
	v_add_f32_e32 v25, 1.0, v25
	v_pk_fma_f32 v[10:11], v[10:11], v[78:79], v[22:23]
	v_rcp_f32_e32 v26, v25
	v_fma_f32 v25, v27, s97, 1.0
	v_fma_f32 v27, v28, s97, 1.0
	v_pk_fma_f32 v[8:9], v[72:73], v[16:17], v[8:9]
	v_pk_fma_f32 v[10:11], v[74:75], v[18:19], v[10:11]
	v_mul_f32_e32 v27, v14, v27
	v_fma_f32 v28, v29, s97, 1.0
	v_pk_mul_f32 v[16:17], v[8:9], v[8:9]
	v_pk_mul_f32 v[18:19], v[10:11], v[10:11]
	v_mul_f32_e32 v25, v13, v25
	v_mul_f32_e32 v27, 0xc0135761, v27
	v_mul_f32_e32 v28, v15, v28
	v_fma_f32 v16, v16, s97, 1.0
	v_fma_f32 v17, v17, s97, 1.0
	v_fma_f32 v18, v18, s97, 1.0
	v_fma_f32 v19, v19, s97, 1.0
	v_mul_f32_e32 v25, 0xc0135761, v25
	v_exp_f32_e32 v27, v27
	v_mul_f32_e32 v28, 0xc0135761, v28
	v_mul_f32_e32 v16, v8, v16
	v_mul_f32_e32 v17, v9, v17
	v_mul_f32_e32 v18, v10, v18
	v_mul_f32_e32 v19, v11, v19
	v_exp_f32_e32 v25, v25
	v_exp_f32_e32 v29, v28
	v_mul_f32_e32 v16, 0xc0135761, v16
	v_mul_f32_e32 v17, 0xc0135761, v17
	v_mul_f32_e32 v18, 0xc0135761, v18
	v_mul_f32_e32 v19, 0xc0135761, v19
	v_exp_f32_e32 v16, v16
	v_exp_f32_e32 v17, v17
	v_exp_f32_e32 v18, v18
	v_exp_f32_e32 v19, v19
	v_add_f32_e32 v27, 1.0, v27
	v_add_f32_e32 v25, 1.0, v25
	v_rcp_f32_e32 v28, v27
	v_add_f32_e32 v27, 1.0, v29
	v_rcp_f32_e32 v29, v27
	v_rcp_f32_e32 v27, v25
	v_add_f32_e32 v16, 1.0, v16
	v_add_f32_e32 v17, 1.0, v17
	v_add_f32_e32 v18, 1.0, v18
	v_add_f32_e32 v19, 1.0, v19
	v_rcp_f32_e32 v16, v16
	v_rcp_f32_e32 v18, v18
	v_rcp_f32_e32 v19, v19
	v_rcp_f32_e32 v17, v17
	v_pk_mul_f32 v[12:13], v[12:13], v[26:27]
	v_ashrrev_i32_e32 v25, 31, v24
	v_pk_mul_f32 v[4:5], v[4:5], v[12:13]
	v_pk_mul_f32 v[10:11], v[10:11], v[18:19]
	v_pk_mul_f32 v[8:9], v[8:9], v[16:17]
	v_pk_mul_f32 v[10:11], v[2:3], v[10:11]
	v_pk_mul_f32 v[2:3], v[0:1], v[8:9]
	v_cvt_pk_bf16_f32 v0, v4, v5
	v_lshlrev_b64 v[4:5], 13, v[24:25]
	v_lshl_add_u64 v[4:5], s[44:45], 0, v[4:5]
	v_pk_mul_f32 v[14:15], v[14:15], v[28:29]
	v_lshl_add_u64 v[4:5], v[176:177], 1, v[4:5]
	v_pk_mul_f32 v[6:7], v[6:7], v[14:15]
	s_nop 0
	v_cvt_pk_bf16_f32 v1, v6, v7
	v_cvt_pk_bf16_f32 v2, v2, v3
	v_cvt_pk_bf16_f32 v3, v10, v11
	global_store_dwordx4 v[4:5], v[0:3], off nt
